# prep: norm-weight scalar loads no longer waited one by one (multiply deferred to LDS write); gla_light Sinit staging issues its 16 loads at once
# speedup vs baseline: 1.0131x; 1.0131x over previous
; #define LAS __attribute__((address_space(3)))
; __device__ __forceinline__ void gla_light(LAS unsigned char* lds, const Params& p, int layer) {
;     ...
;         __syncthreads();
; #pragma unroll
;         for (int it = 0; it < 8; ++it) { const int pi = tid + 512 * it, row = pi >> 4, seg = pi & 15;
;             const u32x4 vf_ = *(const u32x4*)(E + (size_t)(scanf * 32 + grp) * 32768 + row * 128 + seg * 8);
;             const u32x4 vb_ = *(const u32x4*)(E + (size_t)((scanf + 1) * 32 + grp) * 32768 + row * 128 + seg * 8);
;             *(LAS u32x4*)(lds + SSTF + row * 272 + seg * 16) = vf_; *(LAS u32x4*)(lds + SSTB + row * 272 + seg * 16) = vb_; }
;         __syncthreads();
;         f32x4 gn[8];
; #pragma unroll
;         for (int n = 0; n < 8; ++n) gn[n] = *(const f32x4*)(p.gla_norm + layer * 1024 + h * 256 + hv * 128 + n * 16 + 4 * fq);
.LBB0_426:
	s_ashr_i32 s3, s4, 7
	s_bfe_u32 s2, s4, 0x20005
	s_lshl_b32 s6, s3, 8
	s_lshl_b32 s7, s2, 6
	s_and_b32 s5, s4, 31
	s_or_b32 s6, s7, s6
	s_or_b32 s6, s6, s5
	s_ashr_i32 s7, s6, 31
	s_lshl_b64 s[8:9], s[6:7], 16
	s_or_b32 s6, s6, 32
	s_ashr_i32 s7, s6, 31
	v_lshl_add_u64 v[8:9], v[60:61], 0, s[8:9]
	s_lshl_b64 s[6:7], s[6:7], 16
	v_lshl_add_u64 v[10:11], v[60:61], 0, s[6:7]
	v_lshl_add_u64 v[0:1], v[8:9], 0, v[70:71]
	s_barrier
	v_lshl_add_u64 v[0:1], v[8:9], 0, v[70:71]
	global_load_dwordx4 v[0:3], v[0:1], off
	v_lshl_add_u64 v[4:5], v[10:11], 0, v[70:71]
	global_load_dwordx4 v[4:7], v[4:5], off
	v_lshl_add_u64 v[12:13], v[8:9], 0, v[72:73]
	global_load_dwordx4 v[12:15], v[12:13], off
	v_lshl_add_u64 v[16:17], v[10:11], 0, v[72:73]
	global_load_dwordx4 v[16:19], v[16:17], off
	v_lshl_add_u64 v[20:21], v[8:9], 0, v[74:75]
	global_load_dwordx4 v[20:23], v[20:21], off
	v_lshl_add_u64 v[24:25], v[10:11], 0, v[74:75]
	global_load_dwordx4 v[24:27], v[24:25], off
	v_lshl_add_u64 v[32:33], v[8:9], 0, v[76:77]
	global_load_dwordx4 v[32:35], v[32:33], off
	v_lshl_add_u64 v[36:37], v[10:11], 0, v[76:77]
	global_load_dwordx4 v[36:39], v[36:37], off
	v_lshl_add_u64 v[40:41], v[8:9], 0, v[78:79]
	global_load_dwordx4 v[40:43], v[40:41], off
	v_lshl_add_u64 v[44:45], v[10:11], 0, v[78:79]
	global_load_dwordx4 v[44:47], v[44:45], off
	v_lshl_add_u64 v[48:49], v[8:9], 0, v[80:81]
	global_load_dwordx4 v[48:51], v[48:49], off
	v_lshl_add_u64 v[52:53], v[10:11], 0, v[80:81]
	global_load_dwordx4 v[52:55], v[52:53], off
	v_lshl_add_u64 v[56:57], v[8:9], 0, v[82:83]
	global_load_dwordx4 v[56:59], v[56:57], off
	v_lshl_add_u64 v[96:97], v[10:11], 0, v[82:83]
	global_load_dwordx4 v[96:99], v[96:97], off
	v_lshl_add_u64 v[100:101], v[8:9], 0, v[84:85]
	global_load_dwordx4 v[100:103], v[100:101], off
	v_lshl_add_u64 v[104:105], v[10:11], 0, v[84:85]
	global_load_dwordx4 v[104:107], v[104:105], off
	s_lshl_b32 s6, s2, 10
	s_mov_b32 s7, s69
	v_lshl_add_u64 v[28:29], v[62:63], 0, s[6:7]
	s_lshl_b32 s68, s2, 8
	s_lshl_b32 s6, s3, 14
	s_lshl_b32 s5, s5, 9
	s_lshl_b32 s2, s2, 9
	s_mov_b32 s3, s69
	v_lshl_add_u64 v[90:91], v[68:69], 0, s[2:3]
	s_or_b32 s2, s5, s6
	v_lshl_add_u64 v[86:87], v[64:65], 0, s[68:69]
	v_lshl_add_u64 v[88:89], v[66:67], 0, s[68:69]
	v_or_b32_e32 v92, s2, v132
	s_mov_b32 s5, 0
	s_lshl_b32 s68, s68, 1
	s_waitcnt vmcnt(15)
	v_add_u32_e32 v94, v130, v138
	ds_write_b128 v94, v[0:3]
	s_waitcnt vmcnt(14)
	v_add_u32_e32 v95, v131, v138
	ds_write_b128 v95, v[4:7]
	s_waitcnt vmcnt(13)
	v_add_u32_e32 v94, v130, v139
	ds_write_b128 v94, v[12:15]
	s_waitcnt vmcnt(12)
	v_add_u32_e32 v95, v131, v139
	ds_write_b128 v95, v[16:19]
	s_waitcnt vmcnt(11)
	v_add_u32_e32 v94, v130, v140
	ds_write_b128 v94, v[20:23]
	s_waitcnt vmcnt(10)
	v_add_u32_e32 v95, v131, v140
	ds_write_b128 v95, v[24:27]
	s_waitcnt vmcnt(9)
	v_add_u32_e32 v94, v130, v141
	ds_write_b128 v94, v[32:35]
	s_waitcnt vmcnt(8)
	v_add_u32_e32 v95, v131, v141
	ds_write_b128 v95, v[36:39]
	s_waitcnt vmcnt(7)
	v_add_u32_e32 v94, v130, v142
	ds_write_b128 v94, v[40:43]
	s_waitcnt vmcnt(6)
	v_add_u32_e32 v95, v131, v142
	ds_write_b128 v95, v[44:47]
	s_waitcnt vmcnt(5)
	v_add_u32_e32 v94, v130, v143
	ds_write_b128 v94, v[48:51]
	s_waitcnt vmcnt(4)
	v_add_u32_e32 v95, v131, v143
	ds_write_b128 v95, v[52:55]
	s_waitcnt vmcnt(3)
	v_add_u32_e32 v94, v130, v156
	ds_write_b128 v94, v[56:59]
	s_waitcnt vmcnt(2)
	v_add_u32_e32 v95, v131, v156
	ds_write_b128 v95, v[96:99]
	s_waitcnt vmcnt(1)
	v_add_u32_e32 v94, v130, v157
	ds_write_b128 v94, v[100:103]
	s_waitcnt vmcnt(0)
	v_add_u32_e32 v95, v131, v157
	ds_write_b128 v95, v[104:107]
	s_waitcnt lgkmcnt(0)
	s_barrier
	global_load_dwordx4 v[0:3], v[28:29], off
	global_load_dwordx4 v[4:7], v[28:29], off offset:64
	global_load_dwordx4 v[8:11], v[28:29], off offset:128
	global_load_dwordx4 v[12:15], v[28:29], off offset:192
	global_load_dwordx4 v[16:19], v[28:29], off offset:256
	global_load_dwordx4 v[20:23], v[28:29], off offset:320
	global_load_dwordx4 v[24:27], v[28:29], off offset:384
	s_nop 0
	global_load_dwordx4 v[28:31], v[28:29], off offset:448
	s_branch .LBB0_428

; __device__ __forceinline__ int bid_() { int v = __builtin_amdgcn_readfirstlane((int)blockIdx.x); asm volatile("" : "+s"(v)); return v; }
; #define PREP_LOAD(W_) do { _Pragma("unroll") for (int ps = 0; ps < 4; ++ps) { const int kk = (tid >> 3) + 64 * ps, c4 = (tid & 7) * 4; \
;             v[ps] = (f32x4){0.f, 0.f, 0.f, 0.f}; \
;             if (kk >= (W_).vlo && kk < (W_).vhi) { v[ps] = *(const f32x4*)((W_).src + (size_t)kk * (W_).ld + c4); if ((W_).g) v[ps] = v[ps] * (W_).g[kk]; } } } while (0)
; __device__ __forceinline__ void phase_prep(LAS unsigned char* lds, const Params& p) {
;     ...
;         int job = bid_();
;         if (job < 2 * 2112) { w = wjob_decode(p, job / 2112, job % 2112); PREP_LOAD(w); }
.LBB0_638:
	v_lshlrev_b32_e32 v0, 4, v19
	s_cmp_lg_u64 s[6:7], 0
	v_ashrrev_i32_e32 v8, 3, v19
	v_and_b32_e32 v146, 0x70, v0
	s_cselect_b64 s[4:5], -1, 0
	v_lshl_add_u64 v[16:17], s[10:11], 0, v[146:147]
	v_cmp_lt_i32_e32 vcc, -1, v8
	v_cmp_gt_i32_e64 s[10:11], s17, v8
	v_cndmask_b32_e64 v1, 0, 1, s[4:5]
	s_and_b64 s[12:13], vcc, s[10:11]
	v_mov_b32_e32 v0, 0
	v_cmp_ne_u32_e64 s[10:11], 1, v1
	v_mov_b32_e32 v4, 0
	v_mov_b32_e32 v5, 0
	v_mov_b32_e32 v6, 0
	v_mov_b32_e32 v7, 0
	v_mov_b32_e32 v64, 1.0
	v_mov_b32_e32 v66, 1.0
	v_mov_b32_e32 v68, 1.0
	v_mov_b32_e32 v70, 1.0
	s_and_saveexec_b64 s[4:5], s[12:13]
	s_cbranch_execz .LBB0_641
	v_mad_u64_u32 v[2:3], s[12:13], s8, v8, 0
	v_mov_b32_e32 v4, v3
	v_mad_u64_u32 v[4:5], s[12:13], s9, v8, v[4:5]
	v_mov_b32_e32 v3, v4
	v_lshl_add_u64 v[2:3], v[2:3], 2, v[16:17]
	global_load_dwordx4 v[4:7], v[2:3], off
	s_and_b64 vcc, exec, s[10:11]
	s_cbranch_vccnz .LBB0_641
	v_mov_b32_e32 v9, v147
	v_lshl_add_u64 v[2:3], v[8:9], 2, s[6:7]
	global_load_dword v64, v[2:3], off
.LBB0_641:
	s_or_b64 exec, exec, s[4:5]
	v_add_u32_e32 v146, 64, v8
	s_movk_i32 s4, 0xffbf
	v_cmp_lt_i32_e32 vcc, s4, v8
	v_cmp_gt_i32_e64 s[12:13], s17, v146
	s_and_b64 s[12:13], vcc, s[12:13]
	v_mov_b32_e32 v1, 0
	v_mov_b32_e32 v2, 0
	v_mov_b32_e32 v3, 0
	s_and_saveexec_b64 s[4:5], s[12:13]
	s_cbranch_execz .LBB0_644
	v_mad_u64_u32 v[0:1], s[12:13], s8, v146, 0
	v_mov_b32_e32 v2, v1
	v_mad_u64_u32 v[2:3], s[12:13], s9, v146, v[2:3]
	v_mov_b32_e32 v1, v2
	v_lshl_add_u64 v[0:1], v[0:1], 2, v[16:17]
	global_load_dwordx4 v[0:3], v[0:1], off
	s_and_b64 vcc, exec, s[10:11]
	s_cbranch_vccnz .LBB0_644
	v_lshl_add_u64 v[10:11], v[146:147], 2, s[6:7]
	global_load_dword v66, v[10:11], off
.LBB0_644:
	s_or_b64 exec, exec, s[4:5]
	v_add_u32_e32 v146, 0x80, v8
	s_movk_i32 s4, 0xff7f
	v_cmp_lt_i32_e32 vcc, s4, v8
	v_cmp_gt_i32_e64 s[12:13], s17, v146
	s_and_b64 s[12:13], vcc, s[12:13]
	v_mov_b32_e32 v11, 0
	v_mov_b32_e32 v12, 0
	v_mov_b32_e32 v13, 0
	v_mov_b32_e32 v14, 0
	v_mov_b32_e32 v15, 0
	s_and_saveexec_b64 s[4:5], s[12:13]
	s_cbranch_execz .LBB0_647
	v_mad_u64_u32 v[12:13], s[12:13], s8, v146, 0
	v_mov_b32_e32 v10, v13
	v_mad_u64_u32 v[14:15], s[12:13], s9, v146, v[10:11]
	v_mov_b32_e32 v13, v14
	v_lshl_add_u64 v[12:13], v[12:13], 2, v[16:17]
	global_load_dwordx4 v[12:15], v[12:13], off
	s_and_b64 vcc, exec, s[10:11]
	s_cbranch_vccnz .LBB0_647
	v_lshl_add_u64 v[20:21], v[146:147], 2, s[6:7]
	global_load_dword v68, v[20:21], off
.LBB0_647:
	s_or_b64 exec, exec, s[4:5]
	v_add_u32_e32 v146, 0xc0, v8
	s_movk_i32 s4, 0xff3f
	v_cmp_lt_i32_e32 vcc, s4, v8
	v_cmp_gt_i32_e64 s[12:13], s17, v146
	s_and_b64 s[12:13], vcc, s[12:13]
	v_mov_b32_e32 v10, 0
	v_mov_b32_e32 v9, 0
	v_mov_b32_e32 v8, 0
	s_and_saveexec_b64 s[4:5], s[12:13]
	s_cbranch_execz .LBB0_650
	v_mad_u64_u32 v[8:9], s[12:13], s8, v146, 0
	v_mov_b32_e32 v10, v9
	v_mad_u64_u32 v[10:11], s[8:9], s9, v146, v[10:11]
	v_mov_b32_e32 v9, v10
	v_lshl_add_u64 v[8:9], v[8:9], 2, v[16:17]
	global_load_dwordx4 v[8:11], v[8:9], off
	s_and_b64 vcc, exec, s[10:11]
	s_cbranch_vccnz .LBB0_650
	v_lshl_add_u64 v[16:17], v[146:147], 2, s[6:7]
	global_load_dword v70, v[16:17], off

; #define LAS __attribute__((address_space(3)))
; __device__ __forceinline__ int nblk_() { int v = __builtin_amdgcn_readfirstlane((int)gridDim.x); asm volatile("" : "+s"(v)); return v; }
; #define PREP_LOAD(W_) do { _Pragma("unroll") for (int ps = 0; ps < 4; ++ps) { const int kk = (tid >> 3) + 64 * ps, c4 = (tid & 7) * 4; \
;             v[ps] = (f32x4){0.f, 0.f, 0.f, 0.f}; \
;             if (kk >= (W_).vlo && kk < (W_).vhi) { v[ps] = *(const f32x4*)((W_).src + (size_t)kk * (W_).ld + c4); if ((W_).g) v[ps] = v[ps] * (W_).g[kk]; } } } while (0)
; __device__ __forceinline__ WJob wjob_decode(const Params& p, int layer, int j) {
;     ...
;     j -= 704;
;     { const int nb = j / 11, kb = j % 11, n0 = nb * 32;
;         w.src = p.w_f2 + (size_t)layer * DFF * 1024 + (size_t)kb * 256 * 1024 + n0; w.ld = 1024;
;         w.dst = (bf16_t*)((char*)W + WO_F2) + (size_t)n0 * DFF + kb * 256; w.ldd = DFF; return w; }
; __device__ __forceinline__ void phase_prep(LAS unsigned char* lds, const Params& p) {
;     ...
;             const int tb = buf * 33792;
; #pragma unroll
;             for (int ps = 0; ps < 4; ++ps) { const int kk = (tid >> 3) + 64 * ps, c4 = (tid & 7) * 4;
; #pragma unroll
;                 for (int e = 0; e < 4; ++e) *(LAS float*)(lds + tb + (kk * 33 + c4 + e) * 4) = v[ps][e]; }
;             __syncthreads();
;             const int nj = job + nblk_();
;             if (nj < 2 * 2112) { wn = wjob_decode(p, nj / 2112, nj % 2112); PREP_LOAD(wn); }
.LBB0_654:
	s_mul_i32 s4, s26, 0x8400
	s_add_i32 s27, s4, 0
	v_add_u32_e32 v28, s27, v30
	s_waitcnt vmcnt(0)
	v_pk_mul_f32 v[6:7], v[6:7], v[64:65] op_sel_hi:[1,0]
	v_pk_mul_f32 v[4:5], v[4:5], v[64:65] op_sel_hi:[1,0]
	v_pk_mul_f32 v[2:3], v[2:3], v[66:67] op_sel_hi:[1,0]
	v_pk_mul_f32 v[0:1], v[0:1], v[66:67] op_sel_hi:[1,0]
	v_pk_mul_f32 v[14:15], v[14:15], v[68:69] op_sel_hi:[1,0]
	v_pk_mul_f32 v[12:13], v[12:13], v[68:69] op_sel_hi:[1,0]
	v_pk_mul_f32 v[10:11], v[10:11], v[70:71] op_sel_hi:[1,0]
	v_pk_mul_f32 v[8:9], v[8:9], v[70:71] op_sel_hi:[1,0]
	ds_write2_b32 v28, v4, v5 offset1:1
	ds_write2_b32 v28, v6, v7 offset0:2 offset1:3
	v_add_u32_e32 v28, s27, v31
	ds_write2_b32 v28, v0, v1 offset1:1
	ds_write2_b32 v28, v2, v3 offset0:2 offset1:3
	v_add_u32_e32 v28, s27, v32
	ds_write2_b32 v28, v12, v13 offset1:1
	ds_write2_b32 v28, v14, v15 offset0:2 offset1:3
	v_add_u32_e32 v28, s27, v33
	s_waitcnt lgkmcnt(0)
	s_mov_b32 s4, s25
	ds_write2_b32 v28, v8, v9 offset1:1
	ds_write2_b32 v28, v10, v11 offset0:2 offset1:3
	s_waitcnt lgkmcnt(0)
	s_barrier
	s_add_i32 s5, s4, s22
	s_cmpk_gt_i32 s5, 0x107f
	s_cbranch_scc1 .LBB0_696
	s_mul_hi_i32 s2, s5, 0x3e0f83e1
	s_lshr_b32 s3, s2, 31
	s_ashr_i32 s2, s2, 9
	s_add_i32 s4, s2, s3
	s_mul_i32 s2, s4, 0x840
	s_sub_i32 s34, s5, s2
	s_ashr_i32 s5, s4, 31
	s_mul_i32 s3, s4, 0x2100000
	v_readlane_b32 s6, v254, 25
	s_mul_hi_i32 s2, s4, 0x2100000
	v_readlane_b32 s7, v254, 26
	s_add_u32 s30, s6, s3
	s_addc_u32 s31, s7, s2
	s_cmpk_gt_i32 s34, 0x1df
	s_mov_b64 s[20:21], -1
	s_cbranch_scc0 .LBB0_676
	s_cmpk_gt_u32 s34, 0x2df
	s_cbranch_scc0 .LBB0_673
	s_cmpk_gt_u32 s34, 0x35f
	s_cbranch_scc0 .LBB0_670
	s_cmpk_gt_u32 s34, 0x39f
	s_cbranch_scc0 .LBB0_667
	s_cmpk_gt_u32 s34, 0x41f
	s_cbranch_scc0 .LBB0_664
	s_cmpk_gt_u32 s34, 0x6df
	s_mov_b64 s[6:7], -1
	s_cbranch_scc0 .LBB0_662
	s_add_i32 s6, s34, 0xf920
	s_and_b32 s2, s6, 0xffff
	s_mul_i32 s2, s2, 0xba2f
	s_lshr_b32 s7, s2, 19
	v_readlane_b32 s2, v254, 23
	v_readlane_b32 s3, v254, 24
	s_load_dwordx2 s[2:3], s[2:3], 0x70
	s_mul_i32 s8, s7, 11
	s_sub_i32 s6, s6, s8
	s_and_b32 s8, s6, 0xffff
	s_mul_i32 s18, s4, 0xb00000
	s_mul_hi_i32 s9, s4, 0xb00000
	s_waitcnt lgkmcnt(0)
	s_add_u32 s18, s2, s18
	s_addc_u32 s9, s3, s9
	s_lshl_b32 s68, s6, 18
	s_lshl_b64 s[2:3], s[68:69], 2
	s_add_u32 s2, s18, s2
	s_addc_u32 s3, s9, s3
	s_lshl_b32 s6, s7, 7
	s_add_u32 s18, s2, s6
	s_addc_u32 s19, s3, 0
	s_mul_i32 s7, s7, 0x2c000
	s_add_u32 s2, s30, s7
	s_addc_u32 s3, s31, 0
	s_lshl_b32 s6, s8, 9
	s_add_u32 s2, s2, s6
	s_addc_u32 s3, s3, 0
	s_add_u32 s2, s2, 0x1b80000
	s_addc_u32 s3, s3, 0
	s_mov_b64 s[6:7], 0

; #define PREP_LOAD(W_) do { _Pragma("unroll") for (int ps = 0; ps < 4; ++ps) { const int kk = (tid >> 3) + 64 * ps, c4 = (tid & 7) * 4; \
;             v[ps] = (f32x4){0.f, 0.f, 0.f, 0.f}; \
;             if (kk >= (W_).vlo && kk < (W_).vhi) { v[ps] = *(const f32x4*)((W_).src + (size_t)kk * (W_).ld + c4); if ((W_).g) v[ps] = v[ps] * (W_).g[kk]; } } } while (0)
; __device__ __forceinline__ void phase_prep(LAS unsigned char* lds, const Params& p) {
;     ...
;             if (nj < 2 * 2112) { wn = wjob_decode(p, nj / 2112, nj % 2112); PREP_LOAD(wn); }
.LBB0_683:
	s_cmp_lg_u64 s[6:7], 0
	s_cselect_b64 s[4:5], -1, 0
	v_cmp_gt_i32_e32 vcc, s20, v16
	v_cndmask_b32_e64 v1, 0, 1, s[4:5]
	v_lshl_add_u64 v[28:29], s[18:19], 0, v[146:147]
	s_and_b64 s[30:31], s[10:11], vcc
	v_mov_b32_e32 v0, 0
	v_cmp_ne_u32_e64 s[18:19], 1, v1
	v_mov_b32_e32 v4, 0
	v_mov_b32_e32 v5, 0
	v_mov_b32_e32 v6, 0
	v_mov_b32_e32 v7, 0
	v_mov_b32_e32 v64, 1.0
	v_mov_b32_e32 v66, 1.0
	v_mov_b32_e32 v68, 1.0
	v_mov_b32_e32 v70, 1.0
	s_and_saveexec_b64 s[4:5], s[30:31]
	s_cbranch_execz .LBB0_686
	v_mad_u64_u32 v[2:3], s[30:31], s8, v16, 0
	v_mov_b32_e32 v4, v3
	v_mad_u64_u32 v[4:5], s[30:31], s9, v16, v[4:5]
	v_mov_b32_e32 v3, v4
	v_lshl_add_u64 v[2:3], v[2:3], 2, v[28:29]
	global_load_dwordx4 v[4:7], v[2:3], off
	s_and_b64 vcc, exec, s[18:19]
	s_cbranch_vccnz .LBB0_686
	v_lshl_add_u64 v[2:3], v[16:17], 2, s[6:7]
	global_load_dword v64, v[2:3], off
.LBB0_686:
	s_or_b64 exec, exec, s[4:5]
	v_cmp_gt_i32_e32 vcc, s20, v22
	s_and_b64 s[30:31], s[12:13], vcc
	v_mov_b32_e32 v1, 0
	v_mov_b32_e32 v2, 0
	v_mov_b32_e32 v3, 0
	s_and_saveexec_b64 s[4:5], s[30:31]
	s_cbranch_execz .LBB0_689
	v_mad_u64_u32 v[0:1], s[30:31], s8, v22, 0
	v_mov_b32_e32 v2, v1
	v_mad_u64_u32 v[2:3], s[30:31], s9, v22, v[2:3]
	v_mov_b32_e32 v1, v2
	v_lshl_add_u64 v[0:1], v[0:1], 2, v[28:29]
	global_load_dwordx4 v[0:3], v[0:1], off
	s_and_b64 vcc, exec, s[18:19]
	s_cbranch_vccnz .LBB0_689
	v_lshl_add_u64 v[8:9], v[22:23], 2, s[6:7]
	global_load_dword v66, v[8:9], off
.LBB0_689:
	s_or_b64 exec, exec, s[4:5]
	v_cmp_gt_i32_e32 vcc, s20, v24
	s_and_b64 s[30:31], s[14:15], vcc
	v_mov_b32_e32 v11, 0
	v_mov_b32_e32 v12, 0
	v_mov_b32_e32 v13, 0
	v_mov_b32_e32 v14, 0
	v_mov_b32_e32 v15, 0
	s_and_saveexec_b64 s[4:5], s[30:31]
	s_cbranch_execz .LBB0_692
	v_mad_u64_u32 v[8:9], s[30:31], s8, v24, 0
	v_mov_b32_e32 v10, v9
	v_mad_u64_u32 v[12:13], s[30:31], s9, v24, v[10:11]
	v_mov_b32_e32 v9, v12
	v_lshl_add_u64 v[8:9], v[8:9], 2, v[28:29]
	global_load_dwordx4 v[12:15], v[8:9], off
	s_and_b64 vcc, exec, s[18:19]
	s_cbranch_vccnz .LBB0_692
	v_lshl_add_u64 v[8:9], v[24:25], 2, s[6:7]
	global_load_dword v68, v[8:9], off
.LBB0_692:
	s_or_b64 exec, exec, s[4:5]
	v_cmp_gt_i32_e32 vcc, s20, v26
	s_and_b64 s[20:21], s[16:17], vcc
	v_mov_b32_e32 v10, 0
	v_mov_b32_e32 v9, 0
	v_mov_b32_e32 v8, 0
	s_and_saveexec_b64 s[4:5], s[20:21]
	s_cbranch_execz .LBB0_695
	v_mad_u64_u32 v[8:9], s[20:21], s8, v26, 0
	v_mov_b32_e32 v10, v9
	v_mad_u64_u32 v[10:11], s[8:9], s9, v26, v[10:11]
	v_mov_b32_e32 v9, v10
	v_lshl_add_u64 v[8:9], v[8:9], 2, v[28:29]
	global_load_dwordx4 v[8:11], v[8:9], off
	s_and_b64 vcc, exec, s[18:19]
	s_cbranch_vccnz .LBB0_695
	v_lshl_add_u64 v[28:29], v[26:27], 2, s[6:7]
	global_load_dword v70, v[28:29], off
